# hgB_unit tail: gate/gain vector loads given their own destinations from a 12-quad spare-register pool and hoisted (was 8 serialized load->wait->use round trips), counted vmcnt; on top of previous
# speedup vs baseline: 1.0149x; 1.0080x over previous
.LBB0_190:
	v_ashrrev_i32_e32 v0, 2, v113
	v_ashrrev_i32_e32 v1, 31, v0
	v_lshl_add_u64 v[0:1], s[54:55], 0, v[0:1]
	v_lshlrev_b32_e32 v4, 6, v113
	v_lshlrev_b64 v[2:3], 11, v[0:1]
	v_and_b32_e32 v135, 0xc0, v4
	v_mov_b64_e32 v[4:5], s[22:23]
	v_lshl_add_u64 v[2:3], s[78:79], 0, v[2:3]
	v_lshlrev_b32_e32 v128, 1, v135
	v_mad_u64_u32 v[4:5], s[2:3], v0, s93, v[4:5]
	v_lshl_add_u64 v[2:3], v[2:3], 0, v[128:129]
	s_mov_b32 s2, 0x3824000
	v_add_co_u32_e32 v22, vcc, s2, v2
	v_mad_i32_i24 v5, v1, s93, v5
	s_nop 0
	v_addc_co_u32_e32 v23, vcc, 0, v3, vcc
	s_waitcnt vmcnt(0)
	s_barrier
	v_lshl_add_u64 v[0:1], v[4:5], 0, v[128:129]
	global_load_dwordx2 v[4:5], v[22:23], off offset:3584 sc1
	global_load_dwordx2 v[6:7], v[0:1], off sc1
	s_mov_b64 s[2:3], 0x3824e00
	v_lshl_add_u64 v[20:21], v[2:3], 0, s[2:3]
	global_load_dwordx2 v[2:3], v[20:21], off offset:8 sc1
	global_load_dwordx2 v[8:9], v[0:1], off offset:8 sc1
	global_load_dwordx2 v[10:11], v[20:21], off offset:16 sc1
	global_load_dwordx2 v[12:13], v[0:1], off offset:16 sc1
	global_load_dwordx2 v[14:15], v[20:21], off offset:24 sc1
	global_load_dwordx2 v[16:17], v[0:1], off offset:24 sc1
	global_load_dwordx2 v[18:19], v[20:21], off offset:32 sc1
	global_load_dwordx2 v[24:25], v[0:1], off offset:32 sc1
	global_load_dwordx2 v[26:27], v[20:21], off offset:40 sc1
	global_load_dwordx2 v[28:29], v[0:1], off offset:40 sc1
	global_load_dwordx2 v[30:31], v[20:21], off offset:48 sc1
	global_load_dwordx2 v[32:33], v[0:1], off offset:48 sc1
	global_load_dwordx2 v[34:35], v[20:21], off offset:56 sc1
	global_load_dwordx2 v[36:37], v[0:1], off offset:56 sc1
	global_load_dwordx2 v[38:39], v[20:21], off offset:64 sc1
	global_load_dwordx2 v[40:41], v[0:1], off offset:64 sc1
	global_load_dwordx2 v[44:45], v[20:21], off offset:72 sc1
	global_load_dwordx2 v[46:47], v[0:1], off offset:72 sc1
	global_load_dwordx2 v[48:49], v[20:21], off offset:80 sc1
	global_load_dwordx2 v[50:51], v[0:1], off offset:80 sc1
	global_load_dwordx2 v[52:53], v[20:21], off offset:88 sc1
	global_load_dwordx2 v[56:57], v[0:1], off offset:88 sc1
	global_load_dwordx2 v[58:59], v[20:21], off offset:96 sc1
	global_load_dwordx2 v[60:61], v[0:1], off offset:96 sc1
	global_load_dwordx2 v[62:63], v[20:21], off offset:104 sc1
	global_load_dwordx2 v[70:71], v[0:1], off offset:104 sc1
	s_mov_b64 s[2:3], 0x1d00
	v_lshlrev_b32_e32 v128, 2, v135
	v_readlane_b32 s38, v255, 18
	v_readlane_b32 s39, v255, 19
	v_readlane_b32 s58, v255, 20
	v_readlane_b32 s59, v255, 21
	s_mov_b32 s60, 0xec801000
	s_waitcnt vmcnt(25)
	v_lshlrev_b32_e32 v170, 16, v2
	s_waitcnt vmcnt(24)
	v_lshlrev_b32_e32 v172, 16, v8
	v_and_b32_e32 v171, 0xffff0000, v2
	v_and_b32_e32 v173, 0xffff0000, v8
	v_lshlrev_b32_e32 v174, 16, v3
	v_lshlrev_b32_e32 v176, 16, v9
	v_and_b32_e32 v175, 0xffff0000, v3
	v_and_b32_e32 v177, 0xffff0000, v9
	s_waitcnt vmcnt(23)
	v_lshlrev_b32_e32 v86, 16, v10
	v_and_b32_e32 v87, 0xffff0000, v10
	v_add_co_u32_e32 v10, vcc, s86, v0
	v_lshlrev_b32_e32 v72, 16, v11
	v_and_b32_e32 v73, 0xffff0000, v11
	v_addc_co_u32_e32 v11, vcc, 0, v1, vcc
	v_cmp_lt_i32_e32 vcc, v206, v205
	s_waitcnt vmcnt(18)
	v_lshlrev_b32_e32 v98, 16, v24
	v_and_b32_e32 v99, 0xffff0000, v24
	v_lshlrev_b32_e32 v148, 16, v25
	v_and_b32_e32 v149, 0xffff0000, v25
	v_lshlrev_b32_e32 v78, 16, v4
	v_lshlrev_b32_e32 v88, 16, v6
	v_and_b32_e32 v79, 0xffff0000, v4
	v_and_b32_e32 v89, 0xffff0000, v6
	v_lshlrev_b32_e32 v166, 16, v5
	v_lshlrev_b32_e32 v168, 16, v7
	v_and_b32_e32 v167, 0xffff0000, v5
	v_and_b32_e32 v169, 0xffff0000, v7
	global_load_dwordx2 v[2:3], v[20:21], off offset:112 sc1
	global_load_dwordx2 v[4:5], v[0:1], off offset:112 sc1
	global_load_dwordx2 v[6:7], v[20:21], off offset:120 sc1
	global_load_dwordx2 v[8:9], v[0:1], off offset:120 sc1
	global_load_dwordx4 v[162:165], v[10:11], off offset:3328
	v_lshl_add_u64 v[24:25], v[0:1], 0, s[2:3]
	v_cndmask_b32_e32 v0, v204, v206, vcc
	v_cmp_lt_i32_e32 vcc, v207, v205
	v_lshlrev_b32_e32 v137, 2, v0
	v_lshlrev_b32_e32 v154, 16, v12
	v_cndmask_b32_e32 v0, v204, v207, vcc
	v_and_b32_e32 v155, 0xffff0000, v12
	v_lshlrev_b32_e32 v156, 16, v13
	v_and_b32_e32 v157, 0xffff0000, v13
	v_lshlrev_b32_e32 v54, 16, v14
	v_lshlrev_b32_e32 v158, 16, v16
	v_and_b32_e32 v55, 0xffff0000, v14
	v_and_b32_e32 v159, 0xffff0000, v16
	v_lshlrev_b32_e32 v42, 16, v15
	v_lshlrev_b32_e32 v160, 16, v17
	v_and_b32_e32 v43, 0xffff0000, v15
	v_and_b32_e32 v161, 0xffff0000, v17
	v_lshlrev_b32_e32 v80, 16, v18
	v_and_b32_e32 v81, 0xffff0000, v18
	v_lshlrev_b32_e32 v90, 16, v19
	v_and_b32_e32 v91, 0xffff0000, v19
	s_waitcnt vmcnt(20)
	v_lshlrev_b32_e32 v116, 16, v30
	s_waitcnt vmcnt(19)
	v_lshlrev_b32_e32 v126, 16, v32
	v_and_b32_e32 v117, 0xffff0000, v30
	v_and_b32_e32 v127, 0xffff0000, v32
	v_lshlrev_b32_e32 v100, 16, v31
	v_lshlrev_b32_e32 v140, 16, v33
	v_and_b32_e32 v101, 0xffff0000, v31
	v_and_b32_e32 v141, 0xffff0000, v33
	s_waitcnt vmcnt(18)
	v_lshlrev_b32_e32 v84, 16, v34
	s_waitcnt vmcnt(17)
	v_lshlrev_b32_e32 v142, 16, v36
	v_and_b32_e32 v85, 0xffff0000, v34
	v_and_b32_e32 v143, 0xffff0000, v36
	v_lshlrev_b32_e32 v144, 16, v35
	v_lshlrev_b32_e32 v146, 16, v37
	v_and_b32_e32 v145, 0xffff0000, v35
	v_and_b32_e32 v147, 0xffff0000, v37
	s_waitcnt vmcnt(14)
	v_lshlrev_b32_e32 v102, 16, v44
	v_and_b32_e32 v103, 0xffff0000, v44
	v_lshlrev_b32_e32 v96, 16, v45
	v_and_b32_e32 v97, 0xffff0000, v45
	s_waitcnt vmcnt(12)
	v_lshlrev_b32_e32 v76, 16, v48
	v_and_b32_e32 v77, 0xffff0000, v48
	v_lshlrev_b32_e32 v92, 16, v49
	v_and_b32_e32 v93, 0xffff0000, v49
	v_lshlrev_b32_e32 v135, 2, v0
	v_lshlrev_b32_e32 v112, 16, v38
	v_and_b32_e32 v113, 0xffff0000, v38
	v_lshlrev_b32_e32 v118, 16, v39
	v_and_b32_e32 v119, 0xffff0000, v39
	s_waitcnt vmcnt(8)
	v_lshlrev_b32_e32 v38, 16, v58
	v_and_b32_e32 v39, 0xffff0000, v58
	v_lshlrev_b32_e32 v114, 16, v40
	v_and_b32_e32 v115, 0xffff0000, v40
	v_lshlrev_b32_e32 v120, 16, v41
	v_and_b32_e32 v121, 0xffff0000, v41
	v_lshlrev_b32_e32 v82, 16, v50
	v_and_b32_e32 v83, 0xffff0000, v50
	v_lshlrev_b32_e32 v94, 16, v51
	v_and_b32_e32 v95, 0xffff0000, v51
	v_lshlrev_b32_e32 v104, 16, v52
	v_and_b32_e32 v105, 0xffff0000, v52
	v_lshlrev_b32_e32 v108, 16, v53
	v_and_b32_e32 v109, 0xffff0000, v53
	s_waitcnt vmcnt(7)
	v_lshlrev_b32_e32 v40, 16, v60
	v_and_b32_e32 v41, 0xffff0000, v60
	v_lshlrev_b32_e32 v50, 16, v59
	v_lshlrev_b32_e32 v52, 16, v61
	v_and_b32_e32 v51, 0xffff0000, v59
	v_and_b32_e32 v53, 0xffff0000, v61
	s_waitcnt vmcnt(6)
	v_lshlrev_b32_e32 v60, 16, v62
	v_and_b32_e32 v61, 0xffff0000, v62
	v_lshlrev_b32_e32 v68, 16, v63
	v_and_b32_e32 v69, 0xffff0000, v63
	v_lshlrev_b32_e32 v74, 16, v26
	v_lshlrev_b32_e32 v150, 16, v28
	s_waitcnt vmcnt(4)
	v_lshlrev_b32_e32 v16, 16, v2
	s_waitcnt vmcnt(3)
	v_lshlrev_b32_e32 v18, 16, v4
	v_and_b32_e32 v17, 0xffff0000, v2
	v_and_b32_e32 v19, 0xffff0000, v4
	v_lshlrev_b32_e32 v30, 16, v3
	v_lshlrev_b32_e32 v32, 16, v5
	v_and_b32_e32 v31, 0xffff0000, v3
	v_and_b32_e32 v33, 0xffff0000, v5
	s_waitcnt vmcnt(2)
	v_lshlrev_b32_e32 v34, 16, v6
	s_waitcnt vmcnt(1)
	v_lshlrev_b32_e32 v36, 16, v8
	v_and_b32_e32 v35, 0xffff0000, v6
	v_and_b32_e32 v37, 0xffff0000, v8
	v_lshlrev_b32_e32 v44, 16, v7
	v_lshlrev_b32_e32 v48, 16, v9
	v_and_b32_e32 v45, 0xffff0000, v7
	v_and_b32_e32 v49, 0xffff0000, v9
	global_load_dwordx4 v[224:227], v[24:25], off offset:32
	global_load_dwordx4 v[182:185], v[24:25], off offset:16
	global_load_dwordx4 v[186:189], v128, s[0:1] offset:16
	global_load_dwordx4 v[178:181], v128, s[0:1]
	global_load_dwordx4 v[228:231], v[24:25], off offset:48
	global_load_dwordx4 v[190:193], v[24:25], off offset:64
	global_load_dwordx4 v[194:197], v128, s[0:1] offset:32
	global_load_dwordx4 v[220:223], v128, s[0:1] offset:48
	global_load_dwordx4 v[232:235], v128, s[0:1] offset:64
	global_load_dwordx4 v[236:239], v128, s[0:1] offset:80
	global_load_dwordx4 v[244:247], v128, s[0:1] offset:96
	global_load_dwordx4 v[248:251], v128, s[0:1] offset:112
	s_waitcnt vmcnt(12)
	v_lshlrev_b32_e32 v58, 16, v164
	v_and_b32_e32 v59, 0xffff0000, v164
	v_mul_f32_e32 v62, 0xbfb8aa3b, v58
	v_exp_f32_e32 v62, v62
	v_mul_f32_e32 v63, 0xbfb8aa3b, v59
	v_and_b32_e32 v75, 0xffff0000, v26
	v_and_b32_e32 v151, 0xffff0000, v28
	v_lshlrev_b32_e32 v66, 16, v27
	v_lshlrev_b32_e32 v152, 16, v29
	v_and_b32_e32 v67, 0xffff0000, v27
	v_and_b32_e32 v153, 0xffff0000, v29
	v_pk_add_f32 v[26:27], v[174:175], v[176:177]
	v_pk_add_f32 v[28:29], v[170:171], v[172:173]
	v_exp_f32_e32 v63, v63
	v_lshlrev_b32_e32 v106, 16, v56
	v_and_b32_e32 v107, 0xffff0000, v56
	v_lshlrev_b32_e32 v110, 16, v57
	v_and_b32_e32 v111, 0xffff0000, v57
	v_mov_b32_e32 v56, v29
	v_mov_b32_e32 v57, v27
	v_lshlrev_b32_e32 v122, 16, v46
	v_and_b32_e32 v123, 0xffff0000, v46
	v_lshlrev_b32_e32 v124, 16, v47
	v_and_b32_e32 v125, 0xffff0000, v47
	v_mov_b32_e32 v46, v28
	v_mov_b32_e32 v47, v26
	v_pk_mul_f32 v[56:57], v[56:57], v[56:57]
	v_pk_add_f32 v[72:73], v[72:73], v[156:157]
	v_pk_fma_f32 v[56:57], v[46:47], v[46:47], v[56:57]
	v_add_f32_e32 v46, 1.0, v62
	v_lshlrev_b32_e32 v62, 16, v163
	v_add_f32_e32 v47, 1.0, v63
	v_and_b32_e32 v63, 0xffff0000, v163
	v_mul_f32_e32 v163, 0xbfb8aa3b, v62
	v_exp_f32_e32 v163, v163
	v_mul_f32_e32 v164, 0xbfb8aa3b, v63
	v_exp_f32_e32 v164, v164
	v_rcp_f32_e32 v46, v46
	v_add_f32_e32 v163, 1.0, v163
	v_rcp_f32_e32 v170, v163
	v_add_f32_e32 v163, 1.0, v164
	v_rcp_f32_e32 v47, v47
	v_rcp_f32_e32 v171, v163
	v_pk_add_f32 v[172:173], v[56:57], v[56:57] op_sel:[0,1] op_sel_hi:[1,0]
	v_pk_add_f32 v[56:57], v[166:167], v[168:169]
	v_pk_mul_f32 v[46:47], v[46:47], v[58:59]
	v_pk_mul_f32 v[58:59], v[170:171], v[62:63]
	v_pk_add_f32 v[62:63], v[78:79], v[88:89]
	v_lshlrev_b32_e32 v88, 16, v162
	v_and_b32_e32 v89, 0xffff0000, v162
	v_mul_f32_e32 v162, 0xbfb8aa3b, v88
	v_exp_f32_e32 v163, v162
	v_mul_f32_e32 v162, 0xbfb8aa3b, v89
	v_exp_f32_e32 v164, v162
	v_mov_b32_e32 v162, v63
	v_add_f32_e32 v163, 1.0, v163
	v_rcp_f32_e32 v166, v163
	v_add_f32_e32 v163, 1.0, v164
	v_rcp_f32_e32 v167, v163
	v_mov_b32_e32 v163, v57
	v_mov_b32_e32 v78, v62
	v_mov_b32_e32 v79, v56
	v_pk_mul_f32 v[162:163], v[162:163], v[162:163]
	v_pk_add_f32 v[86:87], v[86:87], v[154:155]
	v_pk_fma_f32 v[162:163], v[78:79], v[78:79], v[162:163]
	v_pk_add_f32 v[42:43], v[42:43], v[160:161]
	v_pk_add_f32 v[54:55], v[54:55], v[158:159]
	v_mul_f32_e32 v156, v73, v73
	v_mul_f32_e32 v154, v87, v87
	v_pk_add_f32 v[162:163], v[162:163], v[162:163] op_sel:[0,1] op_sel_hi:[1,0]
	v_pk_mul_f32 v[160:161], v[42:43], v[42:43]
	v_pk_mul_f32 v[158:159], v[54:55], v[54:55]
	v_pk_fma_f32 v[156:157], v[72:73], v[72:73], v[156:157] op_sel_hi:[1,1,0]
	v_pk_fma_f32 v[154:155], v[86:87], v[86:87], v[154:155] op_sel_hi:[1,1,0]
	v_pk_add_f32 v[90:91], v[90:91], v[148:149]
	v_pk_add_f32 v[98:99], v[80:81], v[98:99]
	v_mov_b32_e32 v163, v158
	v_mov_b32_e32 v173, v159
	v_mov_b32_e32 v155, v160
	v_mov_b32_e32 v157, v161
	v_mov_b32_e32 v148, v99
	v_mov_b32_e32 v149, v91
	v_pk_add_f32 v[158:159], v[162:163], v[172:173]
	v_pk_add_f32 v[154:155], v[154:155], v[156:157]
	v_pk_add_f32 v[66:67], v[66:67], v[152:153]
	v_pk_add_f32 v[74:75], v[74:75], v[150:151]
	v_mov_b32_e32 v80, v98
	v_mov_b32_e32 v81, v90
	v_pk_mul_f32 v[148:149], v[148:149], v[148:149]
	v_pk_add_f32 v[154:155], v[158:159], v[154:155]
	v_mul_f32_e32 v152, v67, v67
	v_mul_f32_e32 v150, v75, v75
	v_pk_fma_f32 v[80:81], v[80:81], v[80:81], v[148:149]
	v_pk_add_f32 v[100:101], v[100:101], v[140:141]
	v_pk_add_f32 v[116:117], v[116:117], v[126:127]
	v_pk_add_f32 v[154:155], v[154:155], v[154:155] op_sel:[0,1] op_sel_hi:[1,0]
	v_pk_fma_f32 v[152:153], v[66:67], v[66:67], v[152:153] op_sel_hi:[1,1,0]
	v_pk_fma_f32 v[150:151], v[74:75], v[74:75], v[150:151] op_sel_hi:[1,1,0]
	v_pk_add_f32 v[148:149], v[80:81], v[80:81] op_sel:[0,1] op_sel_hi:[1,0]
	v_pk_add_f32 v[80:81], v[144:145], v[146:147]
	v_pk_add_f32 v[84:85], v[84:85], v[142:143]
	v_pk_mul_f32 v[140:141], v[100:101], v[100:101]
	v_pk_mul_f32 v[126:127], v[116:117], v[116:117]
	v_mov_b32_e32 v144, v85
	v_mov_b32_e32 v145, v81
	v_mov_b32_e32 v151, v140
	v_mov_b32_e32 v153, v141
	v_mov_b32_e32 v155, v126
	v_mov_b32_e32 v149, v127
	v_mov_b32_e32 v142, v84
	v_mov_b32_e32 v143, v80
	v_pk_mul_f32 v[144:145], v[144:145], v[144:145]
	v_pk_add_f32 v[140:141], v[150:151], v[152:153]
	v_pk_add_f32 v[126:127], v[154:155], v[148:149]
	v_pk_add_f32 v[118:119], v[118:119], v[120:121]
	v_pk_add_f32 v[112:113], v[112:113], v[114:115]
	v_pk_fma_f32 v[142:143], v[142:143], v[142:143], v[144:145]
	v_pk_add_f32 v[126:127], v[126:127], v[140:141]
	v_pk_add_f32 v[96:97], v[96:97], v[124:125]
	v_pk_add_f32 v[102:103], v[102:103], v[122:123]
	v_mul_f32_e32 v120, v119, v119
	v_mul_f32_e32 v114, v113, v113
	v_pk_add_f32 v[142:143], v[142:143], v[142:143] op_sel:[0,1] op_sel_hi:[1,0]
	v_pk_add_f32 v[126:127], v[126:127], v[126:127] op_sel:[0,1] op_sel_hi:[1,0]
	v_pk_mul_f32 v[124:125], v[96:97], v[96:97]
	v_pk_mul_f32 v[122:123], v[102:103], v[102:103]
	v_pk_fma_f32 v[120:121], v[118:119], v[118:119], v[120:121] op_sel_hi:[1,1,0]
	v_pk_fma_f32 v[114:115], v[112:113], v[112:113], v[114:115] op_sel_hi:[1,1,0]
	v_pk_add_f32 v[92:93], v[92:93], v[94:95]
	v_pk_add_f32 v[76:77], v[76:77], v[82:83]
	v_mov_b32_e32 v127, v122
	v_mov_b32_e32 v143, v123
	v_mov_b32_e32 v115, v124
	v_mov_b32_e32 v121, v125
	v_mov_b32_e32 v94, v77
	v_mov_b32_e32 v95, v93
	v_pk_add_f32 v[122:123], v[126:127], v[142:143]
	v_pk_add_f32 v[114:115], v[114:115], v[120:121]
	v_pk_add_f32 v[108:109], v[108:109], v[110:111]
	v_pk_add_f32 v[104:105], v[104:105], v[106:107]
	v_mov_b32_e32 v82, v76
	v_mov_b32_e32 v83, v92
	v_pk_mul_f32 v[94:95], v[94:95], v[94:95]
	v_pk_add_f32 v[114:115], v[122:123], v[114:115]
	v_mul_f32_e32 v110, v109, v109
	v_mul_f32_e32 v106, v105, v105
	v_pk_fma_f32 v[82:83], v[82:83], v[82:83], v[94:95]
	v_pk_add_f32 v[50:51], v[50:51], v[52:53]
	v_pk_add_f32 v[40:41], v[38:39], v[40:41]
	v_lshlrev_b32_e32 v64, 16, v70
	v_and_b32_e32 v65, 0xffff0000, v70
	v_lshlrev_b32_e32 v70, 16, v71
	v_and_b32_e32 v71, 0xffff0000, v71
	v_pk_add_f32 v[114:115], v[114:115], v[114:115] op_sel:[0,1] op_sel_hi:[1,0]
	v_pk_fma_f32 v[110:111], v[108:109], v[108:109], v[110:111] op_sel_hi:[1,1,0]
	v_pk_fma_f32 v[106:107], v[104:105], v[104:105], v[106:107] op_sel_hi:[1,1,0]
	v_pk_add_f32 v[82:83], v[82:83], v[82:83] op_sel:[0,1] op_sel_hi:[1,0]
	v_pk_mul_f32 v[52:53], v[50:51], v[50:51]
	v_pk_mul_f32 v[38:39], v[40:41], v[40:41]
	v_pk_add_f32 v[68:69], v[68:69], v[70:71]
	v_pk_add_f32 v[60:61], v[60:61], v[64:65]
	v_mov_b32_e32 v107, v52
	v_mov_b32_e32 v111, v53
	v_mov_b32_e32 v115, v38
	v_mov_b32_e32 v83, v39
	v_mov_b32_e32 v70, v61
	v_mov_b32_e32 v71, v69
	v_pk_add_f32 v[52:53], v[106:107], v[110:111]
	v_pk_add_f32 v[38:39], v[114:115], v[82:83]
	v_mov_b32_e32 v64, v60
	v_mov_b32_e32 v65, v68
	v_pk_mul_f32 v[70:71], v[70:71], v[70:71]
	v_pk_add_f32 v[38:39], v[38:39], v[52:53]
	v_pk_add_f32 v[34:35], v[34:35], v[36:37]
	v_pk_add_f32 v[32:33], v[30:31], v[32:33]
	v_pk_add_f32 v[36:37], v[16:17], v[18:19]
	v_pk_fma_f32 v[64:65], v[64:65], v[64:65], v[70:71]
	v_pk_add_f32 v[52:53], v[38:39], v[38:39] op_sel:[0,1] op_sel_hi:[1,0]
	v_pk_add_f32 v[38:39], v[44:45], v[48:49]
	v_mul_f32_e32 v30, v33, v33
	v_mul_f32_e32 v16, v37, v37
	v_pk_add_f32 v[64:65], v[64:65], v[64:65] op_sel:[0,1] op_sel_hi:[1,0]
	v_pk_mul_f32 v[44:45], v[38:39], v[38:39]
	v_pk_mul_f32 v[48:49], v[34:35], v[34:35]
	v_pk_fma_f32 v[30:31], v[32:33], v[32:33], v[30:31] op_sel_hi:[1,1,0]
	v_pk_fma_f32 v[16:17], v[36:37], v[36:37], v[16:17] op_sel_hi:[1,1,0]
	v_mov_b32_e32 v53, v48
	v_mov_b32_e32 v65, v49
	v_mov_b32_e32 v17, v44
	v_mov_b32_e32 v31, v45
	v_pk_add_f32 v[18:19], v[52:53], v[64:65]
	v_pk_add_f32 v[16:17], v[16:17], v[30:31]
	v_pk_mul_f32 v[78:79], v[166:167], v[88:89]
	v_pk_add_f32 v[16:17], v[18:19], v[16:17]
	v_lshlrev_b32_e32 v88, 16, v165
	v_add_f32_e32 v16, v16, v17
	ds_bpermute_b32 v17, v137, v16
	v_mul_f32_e32 v18, 0xbfb8aa3b, v88
	v_and_b32_e32 v89, 0xffff0000, v165
	v_exp_f32_e32 v18, v18
	v_mul_f32_e32 v19, 0xbfb8aa3b, v89
	s_waitcnt lgkmcnt(0)
	v_add_f32_e32 v30, v16, v17
	ds_bpermute_b32 v31, v135, v30
	v_exp_f32_e32 v19, v19
	v_add_f32_e32 v16, 1.0, v18
	v_rcp_f32_e32 v16, v16
	s_waitcnt lgkmcnt(0)
	v_add_f32_e32 v18, v30, v31
	v_fmamk_f32 v18, v18, 0x3b800000, v201
	v_add_f32_e32 v17, 1.0, v19
	v_mul_f32_e32 v19, 0x4b800000, v18
	v_cmp_gt_f32_e32 vcc, s19, v18
	v_rcp_f32_e32 v17, v17
	s_nop 0
	v_cndmask_b32_e32 v18, v18, v19, vcc
	v_rsq_f32_e32 v30, v18
	v_pk_mul_f32 v[44:45], v[16:17], v[88:89]
	v_mul_f32_e32 v31, 0x45800000, v30
	v_cndmask_b32_e32 v30, v30, v31, vcc
	v_pk_mul_f32 v[48:49], v[62:63], v[30:31] op_sel_hi:[1,0]
	s_waitcnt vmcnt(8)
	v_pk_mul_f32 v[12:13], v[178:179], v[48:49]
	v_pk_mul_f32 v[48:49], v[56:57], v[30:31] op_sel_hi:[1,0]
	v_pk_mul_f32 v[12:13], v[78:79], v[12:13]
	v_pk_mul_f32 v[14:15], v[180:181], v[48:49]
	global_load_dwordx4 v[178:181], v128, s[0:1] offset:128
	v_cvt_pk_bf16_f32 v12, v12, v13
	v_pk_mul_f32 v[14:15], v[58:59], v[14:15]
	s_nop 0
	v_cvt_pk_bf16_f32 v13, v14, v15
	v_pk_mul_f32 v[14:15], v[28:29], v[30:31] op_sel_hi:[1,0]
	s_waitcnt vmcnt(11)
	v_lshlrev_b32_e32 v28, 16, v183
	s_waitcnt vmcnt(10)
	v_pk_mul_f32 v[8:9], v[186:187], v[14:15]
	v_and_b32_e32 v29, 0xffff0000, v183
	v_pk_mul_f32 v[8:9], v[46:47], v[8:9]
	v_mul_f32_e32 v5, 0xbfb8aa3b, v28
	v_cvt_pk_bf16_f32 v14, v8, v9
	v_pk_mul_f32 v[8:9], v[26:27], v[30:31] op_sel_hi:[1,0]
	v_exp_f32_e32 v5, v5
	v_pk_mul_f32 v[8:9], v[188:189], v[8:9]
	global_load_dwordx4 v[186:189], v[24:25], off offset:80
	v_and_b32_e32 v47, 0xffff0000, v182
	v_pk_mul_f32 v[8:9], v[44:45], v[8:9]
	v_add_f32_e32 v5, 1.0, v5
	v_cvt_pk_bf16_f32 v15, v8, v9
	global_store_dwordx4 v[22:23], v[12:15], off offset:3584
	s_nop 0
	v_lshlrev_b32_e32 v22, 16, v184
	v_and_b32_e32 v23, 0xffff0000, v184
	v_mul_f32_e32 v6, 0xbfb8aa3b, v22
	v_exp_f32_e32 v6, v6
	v_mul_f32_e32 v26, 0xbfb8aa3b, v23
	v_exp_f32_e32 v27, v26
	v_rcp_f32_e32 v44, v5
	v_add_f32_e32 v6, 1.0, v6
	v_rcp_f32_e32 v26, v6
	v_add_f32_e32 v6, 1.0, v27
	v_mul_f32_e32 v27, 0xbfb8aa3b, v29
	v_exp_f32_e32 v31, v27
	v_rcp_f32_e32 v27, v6
	v_mul_f32_e32 v6, 0xbfb8aa3b, v47
	v_exp_f32_e32 v6, v6
	v_add_f32_e32 v5, 1.0, v31
	v_rcp_f32_e32 v45, v5
	v_lshlrev_b32_e32 v46, 16, v182
	v_add_f32_e32 v5, 1.0, v6
	v_lshlrev_b32_e32 v6, 16, v185
	v_and_b32_e32 v7, 0xffff0000, v185
	global_load_dwordx4 v[182:185], v128, s[0:1] offset:144
	v_mul_f32_e32 v31, 0xbfb8aa3b, v6
	v_exp_f32_e32 v31, v31
	v_mul_f32_e32 v48, 0xbfb8aa3b, v7
	v_mul_f32_e32 v4, 0xbfb8aa3b, v46
	v_exp_f32_e32 v49, v48
	v_exp_f32_e32 v4, v4
	v_add_f32_e32 v31, 1.0, v31
	v_rcp_f32_e32 v48, v31
	v_add_f32_e32 v31, 1.0, v49
	v_add_f32_e32 v4, 1.0, v4
	v_rcp_f32_e32 v49, v31
	v_rcp_f32_e32 v4, v4
	v_rcp_f32_e32 v5, v5
	v_pk_mul_f32 v[22:23], v[26:27], v[22:23]
	v_pk_mul_f32 v[26:27], v[44:45], v[28:29]
	v_pk_mul_f32 v[28:29], v[48:49], v[6:7]
	v_pk_mul_f32 v[6:7], v[86:87], v[30:31] op_sel_hi:[1,0]
	v_pk_mul_f32 v[4:5], v[4:5], v[46:47]
	s_waitcnt vmcnt(10)
	v_and_b32_e32 v47, 0xffff0000, v190
	v_lshlrev_b32_e32 v46, 16, v190
	v_mul_f32_e32 v16, 0xbfb8aa3b, v46
	v_exp_f32_e32 v16, v16
	s_waitcnt vmcnt(9)
	v_pk_mul_f32 v[6:7], v[194:195], v[6:7]
	s_nop 0
	v_pk_mul_f32 v[4:5], v[4:5], v[6:7]
	v_pk_mul_f32 v[6:7], v[72:73], v[30:31] op_sel_hi:[1,0]
	v_cvt_pk_bf16_f32 v4, v4, v5
	v_pk_mul_f32 v[6:7], v[196:197], v[6:7]
	global_load_dwordx4 v[194:197], v128, s[0:1] offset:160
	v_pk_mul_f32 v[8:9], v[42:43], v[30:31] op_sel_hi:[1,0]
	v_pk_mul_f32 v[6:7], v[26:27], v[6:7]
	s_waitcnt vmcnt(9)
	v_pk_mul_f32 v[8:9], v[222:223], v[8:9]
	v_cvt_pk_bf16_f32 v5, v6, v7
	v_pk_mul_f32 v[6:7], v[54:55], v[30:31] op_sel_hi:[1,0]
	v_pk_mul_f32 v[8:9], v[28:29], v[8:9]
	v_pk_mul_f32 v[6:7], v[220:221], v[6:7]
	global_load_dwordx4 v[220:223], v128, s[0:1] offset:176
	s_waitcnt vmcnt(17)
	v_lshlrev_b32_e32 v12, 16, v226
	v_pk_mul_f32 v[6:7], v[22:23], v[6:7]
	v_and_b32_e32 v13, 0xffff0000, v226
	v_cvt_pk_bf16_f32 v6, v6, v7
	v_cvt_pk_bf16_f32 v7, v8, v9
	global_store_dwordx4 v[20:21], v[4:7], off offset:16
	s_nop 0
	v_mul_f32_e32 v2, 0xbfb8aa3b, v12
	v_exp_f32_e32 v2, v2
	v_mul_f32_e32 v14, 0xbfb8aa3b, v13
	v_exp_f32_e32 v15, v14
	v_lshlrev_b32_e32 v22, 16, v225
	v_add_f32_e32 v2, 1.0, v2
	v_and_b32_e32 v23, 0xffff0000, v225
	v_mul_f32_e32 v1, 0xbfb8aa3b, v22
	v_rcp_f32_e32 v14, v2
	v_add_f32_e32 v2, 1.0, v15
	v_exp_f32_e32 v1, v1
	v_mul_f32_e32 v15, 0xbfb8aa3b, v23
	v_and_b32_e32 v29, 0xffff0000, v224
	v_exp_f32_e32 v27, v15
	v_rcp_f32_e32 v15, v2
	v_mul_f32_e32 v2, 0xbfb8aa3b, v29
	v_exp_f32_e32 v2, v2
	v_add_f32_e32 v1, 1.0, v1
	v_rcp_f32_e32 v26, v1
	v_add_f32_e32 v1, 1.0, v27
	v_rcp_f32_e32 v27, v1
	v_add_f32_e32 v1, 1.0, v2
	v_lshlrev_b32_e32 v2, 16, v227
	v_and_b32_e32 v3, 0xffff0000, v227
	v_mul_f32_e32 v31, 0xbfb8aa3b, v2
	v_lshlrev_b32_e32 v28, 16, v224
	global_load_dwordx4 v[224:227], v[24:25], off offset:96
	v_exp_f32_e32 v31, v31
	v_mul_f32_e32 v42, 0xbfb8aa3b, v3
	v_mul_f32_e32 v0, 0xbfb8aa3b, v28
	v_exp_f32_e32 v43, v42
	v_exp_f32_e32 v0, v0
	v_add_f32_e32 v31, 1.0, v31
	v_rcp_f32_e32 v42, v31
	v_add_f32_e32 v31, 1.0, v43
	v_add_f32_e32 v0, 1.0, v0
	v_rcp_f32_e32 v43, v31
	v_rcp_f32_e32 v0, v0
	v_rcp_f32_e32 v1, v1
	v_pk_mul_f32 v[12:13], v[14:15], v[12:13]
	v_pk_mul_f32 v[14:15], v[26:27], v[22:23]
	v_pk_mul_f32 v[22:23], v[42:43], v[2:3]
	v_pk_mul_f32 v[2:3], v[98:99], v[30:31] op_sel_hi:[1,0]
	v_pk_mul_f32 v[0:1], v[0:1], v[28:29]
	s_waitcnt vmcnt(15)
	v_lshlrev_b32_e32 v28, 16, v231
	v_and_b32_e32 v29, 0xffff0000, v231
	v_mul_f32_e32 v42, 0xbfb8aa3b, v29
	v_exp_f32_e32 v43, v42
	v_add_f32_e32 v16, 1.0, v16
	v_rcp_f32_e32 v16, v16
	s_waitcnt vmcnt(11)
	v_pk_mul_f32 v[2:3], v[232:233], v[2:3]
	s_nop 0
	v_pk_mul_f32 v[0:1], v[2:3], v[0:1]
	v_pk_mul_f32 v[2:3], v[90:91], v[30:31] op_sel_hi:[1,0]
	v_cvt_pk_bf16_f32 v0, v0, v1
	v_pk_mul_f32 v[2:3], v[234:235], v[2:3]
	global_load_dwordx4 v[232:235], v128, s[0:1] offset:192
	v_pk_mul_f32 v[4:5], v[66:67], v[30:31] op_sel_hi:[1,0]
	v_pk_mul_f32 v[2:3], v[2:3], v[14:15]
	s_waitcnt vmcnt(11)
	v_pk_mul_f32 v[4:5], v[238:239], v[4:5]
	v_cvt_pk_bf16_f32 v1, v2, v3
	v_pk_mul_f32 v[2:3], v[74:75], v[30:31] op_sel_hi:[1,0]
	v_pk_mul_f32 v[4:5], v[4:5], v[22:23]
	v_pk_mul_f32 v[2:3], v[236:237], v[2:3]
	global_load_dwordx4 v[236:239], v128, s[0:1] offset:208
	v_lshlrev_b32_e32 v8, 16, v230
	v_pk_mul_f32 v[2:3], v[2:3], v[12:13]
	v_and_b32_e32 v9, 0xffff0000, v230
	v_cvt_pk_bf16_f32 v2, v2, v3
	v_cvt_pk_bf16_f32 v3, v4, v5
	global_store_dwordx4 v[20:21], v[0:3], off offset:32
	s_nop 0
	v_lshlrev_b32_e32 v12, 16, v229
	v_and_b32_e32 v13, 0xffff0000, v229
	v_lshlrev_b32_e32 v22, 16, v228
	v_and_b32_e32 v23, 0xffff0000, v228
	global_load_dwordx4 v[228:231], v[24:25], off offset:112
	v_mul_f32_e32 v10, 0xbfb8aa3b, v8
	v_mul_f32_e32 v11, 0xbfb8aa3b, v9
	v_mul_f32_e32 v14, 0xbfb8aa3b, v12
	v_mul_f32_e32 v15, 0xbfb8aa3b, v13
	v_mul_f32_e32 v26, 0xbfb8aa3b, v22
	v_mul_f32_e32 v27, 0xbfb8aa3b, v23
	v_exp_f32_e32 v10, v10
	v_exp_f32_e32 v11, v11
	v_exp_f32_e32 v14, v14
	v_exp_f32_e32 v15, v15
	v_exp_f32_e32 v26, v26
	v_exp_f32_e32 v27, v27
	v_mul_f32_e32 v31, 0xbfb8aa3b, v28
	v_exp_f32_e32 v31, v31
	v_add_f32_e32 v10, 1.0, v10
	v_add_f32_e32 v11, 1.0, v11
	v_add_f32_e32 v14, 1.0, v14
	v_add_f32_e32 v15, 1.0, v15
	v_add_f32_e32 v26, 1.0, v26
	v_add_f32_e32 v27, 1.0, v27
	v_rcp_f32_e32 v10, v10
	v_rcp_f32_e32 v11, v11
	v_rcp_f32_e32 v14, v14
	v_rcp_f32_e32 v15, v15
	v_rcp_f32_e32 v26, v26
	v_rcp_f32_e32 v27, v27
	v_add_f32_e32 v31, 1.0, v31
	v_rcp_f32_e32 v42, v31
	v_add_f32_e32 v31, 1.0, v43
	v_pk_mul_f32 v[8:9], v[10:11], v[8:9]
	v_pk_mul_f32 v[10:11], v[14:15], v[12:13]
	v_pk_mul_f32 v[12:13], v[26:27], v[22:23]
	v_pk_mul_f32 v[22:23], v[116:117], v[30:31] op_sel_hi:[1,0]
	v_rcp_f32_e32 v43, v31
	v_lshlrev_b32_e32 v26, 16, v192
	v_and_b32_e32 v27, 0xffff0000, v192
	v_pk_mul_f32 v[14:15], v[42:43], v[28:29]
	v_lshlrev_b32_e32 v42, 16, v191
	v_and_b32_e32 v43, 0xffff0000, v191
	v_mul_f32_e32 v17, 0xbfb8aa3b, v42
	v_exp_f32_e32 v17, v17
	s_waitcnt vmcnt(13)
	v_pk_mul_f32 v[0:1], v[244:245], v[22:23]
	s_nop 0
	v_pk_mul_f32 v[0:1], v[0:1], v[12:13]
	v_pk_mul_f32 v[12:13], v[100:101], v[30:31] op_sel_hi:[1,0]
	v_cvt_pk_bf16_f32 v0, v0, v1
	v_pk_mul_f32 v[2:3], v[246:247], v[12:13]
	global_load_dwordx4 v[244:247], v128, s[0:1] offset:224
	v_mul_f32_e32 v12, 0xbfb8aa3b, v26
	v_pk_mul_f32 v[2:3], v[2:3], v[10:11]
	v_exp_f32_e32 v18, v12
	v_cvt_pk_bf16_f32 v1, v2, v3
	v_pk_mul_f32 v[2:3], v[84:85], v[30:31] op_sel_hi:[1,0]
	v_mul_f32_e32 v12, 0xbfb8aa3b, v27
	s_waitcnt vmcnt(13)
	v_pk_mul_f32 v[2:3], v[2:3], v[248:249]
	v_pk_mul_f32 v[4:5], v[80:81], v[30:31] op_sel_hi:[1,0]
	v_pk_mul_f32 v[2:3], v[2:3], v[8:9]
	v_pk_mul_f32 v[4:5], v[4:5], v[250:251]
	global_load_dwordx4 v[248:251], v128, s[0:1] offset:240
	v_cvt_pk_bf16_f32 v2, v2, v3
	v_pk_mul_f32 v[4:5], v[4:5], v[14:15]
	v_exp_f32_e32 v29, v12
	v_cvt_pk_bf16_f32 v3, v4, v5
	global_store_dwordx4 v[20:21], v[0:3], off offset:48
	s_nop 0
	v_add_f32_e32 v18, 1.0, v18
	v_rcp_f32_e32 v28, v18
	v_add_f32_e32 v18, 1.0, v29
	v_mul_f32_e32 v29, 0xbfb8aa3b, v43
	v_exp_f32_e32 v31, v29
	v_rcp_f32_e32 v29, v18
	v_mul_f32_e32 v18, 0xbfb8aa3b, v47
	v_exp_f32_e32 v18, v18
	s_nop 0
	v_add_f32_e32 v17, 1.0, v17
	v_rcp_f32_e32 v44, v17
	v_add_f32_e32 v17, 1.0, v31
	v_rcp_f32_e32 v45, v17
	v_add_f32_e32 v17, 1.0, v18
	v_lshlrev_b32_e32 v18, 16, v193
	v_and_b32_e32 v19, 0xffff0000, v193
	v_mul_f32_e32 v31, 0xbfb8aa3b, v18
	v_exp_f32_e32 v31, v31
	v_mul_f32_e32 v48, 0xbfb8aa3b, v19
	v_exp_f32_e32 v49, v48
	v_rcp_f32_e32 v17, v17
	v_add_f32_e32 v31, 1.0, v31
	v_rcp_f32_e32 v48, v31
	v_add_f32_e32 v31, 1.0, v49
	v_pk_mul_f32 v[26:27], v[28:29], v[26:27]
	v_pk_mul_f32 v[28:29], v[44:45], v[42:43]
	v_pk_mul_f32 v[42:43], v[112:113], v[30:31] op_sel_hi:[1,0]
	v_pk_mul_f32 v[16:17], v[16:17], v[46:47]
	v_rcp_f32_e32 v49, v31
	s_waitcnt vmcnt(14)
	v_pk_mul_f32 v[4:5], v[42:43], v[178:179]
	s_nop 0
	v_pk_mul_f32 v[4:5], v[4:5], v[16:17]
	v_pk_mul_f32 v[16:17], v[118:119], v[30:31] op_sel_hi:[1,0]
	v_cvt_pk_bf16_f32 v4, v4, v5
	v_pk_mul_f32 v[6:7], v[16:17], v[180:181]
	v_pk_mul_f32 v[18:19], v[48:49], v[18:19]
	v_pk_mul_f32 v[6:7], v[6:7], v[28:29]
	s_waitcnt vmcnt(13)
	v_lshlrev_b32_e32 v16, 16, v188
	v_cvt_pk_bf16_f32 v5, v6, v7
	v_pk_mul_f32 v[6:7], v[102:103], v[30:31] op_sel_hi:[1,0]
	v_and_b32_e32 v17, 0xffff0000, v188
	s_waitcnt vmcnt(11)
	v_pk_mul_f32 v[6:7], v[6:7], v[182:183]
	v_pk_mul_f32 v[8:9], v[96:97], v[30:31] op_sel_hi:[1,0]
	v_pk_mul_f32 v[6:7], v[6:7], v[26:27]
	v_pk_mul_f32 v[8:9], v[8:9], v[184:185]
	v_cvt_pk_bf16_f32 v6, v6, v7
	v_pk_mul_f32 v[8:9], v[8:9], v[18:19]
	v_lshlrev_b32_e32 v26, 16, v187
	v_cvt_pk_bf16_f32 v7, v8, v9
	global_store_dwordx4 v[20:21], v[4:7], off offset:64
	s_nop 0
	v_and_b32_e32 v27, 0xffff0000, v187
	v_mul_f32_e32 v23, 0xbfb8aa3b, v26
	v_exp_f32_e32 v23, v23
	v_mul_f32_e32 v24, 0xbfb8aa3b, v27
	v_exp_f32_e32 v24, v24
	v_and_b32_e32 v43, 0xffff0000, v186
	v_add_f32_e32 v23, 1.0, v23
	v_rcp_f32_e32 v28, v23
	v_add_f32_e32 v23, 1.0, v24
	v_mul_f32_e32 v24, 0xbfb8aa3b, v43
	v_exp_f32_e32 v24, v24
	v_mul_f32_e32 v18, 0xbfb8aa3b, v16
	v_mul_f32_e32 v19, 0xbfb8aa3b, v17
	v_lshlrev_b32_e32 v42, 16, v186
	v_exp_f32_e32 v18, v18
	v_exp_f32_e32 v19, v19
	v_mul_f32_e32 v22, 0xbfb8aa3b, v42
	v_exp_f32_e32 v22, v22
	v_rcp_f32_e32 v29, v23
	v_add_f32_e32 v23, 1.0, v24
	v_lshlrev_b32_e32 v24, 16, v189
	v_and_b32_e32 v25, 0xffff0000, v189
	v_mul_f32_e32 v31, 0xbfb8aa3b, v24
	v_exp_f32_e32 v31, v31
	v_mul_f32_e32 v44, 0xbfb8aa3b, v25
	v_add_f32_e32 v18, 1.0, v18
	v_add_f32_e32 v19, 1.0, v19
	v_exp_f32_e32 v45, v44
	v_rcp_f32_e32 v18, v18
	v_rcp_f32_e32 v19, v19
	v_add_f32_e32 v22, 1.0, v22
	v_rcp_f32_e32 v22, v22
	v_rcp_f32_e32 v23, v23
	v_add_f32_e32 v31, 1.0, v31
	v_rcp_f32_e32 v44, v31
	v_add_f32_e32 v31, 1.0, v45
	v_pk_mul_f32 v[16:17], v[18:19], v[16:17]
	v_pk_mul_f32 v[18:19], v[28:29], v[26:27]
	v_pk_mul_f32 v[26:27], v[76:77], v[30:31] op_sel_hi:[1,0]
	v_pk_mul_f32 v[22:23], v[22:23], v[42:43]
	v_rcp_f32_e32 v45, v31
	s_waitcnt vmcnt(11)
	v_pk_mul_f32 v[4:5], v[26:27], v[194:195]
	s_nop 0
	v_pk_mul_f32 v[4:5], v[4:5], v[22:23]
	v_pk_mul_f32 v[22:23], v[92:93], v[30:31] op_sel_hi:[1,0]
	v_cvt_pk_bf16_f32 v4, v4, v5
	v_pk_mul_f32 v[6:7], v[22:23], v[196:197]
	v_pk_mul_f32 v[24:25], v[44:45], v[24:25]
	v_pk_mul_f32 v[6:7], v[6:7], v[18:19]
	v_pk_mul_f32 v[22:23], v[40:41], v[30:31] op_sel_hi:[1,0]
	v_cvt_pk_bf16_f32 v5, v6, v7
	v_pk_mul_f32 v[6:7], v[104:105], v[30:31] op_sel_hi:[1,0]
	s_waitcnt vmcnt(10)
	v_pk_mul_f32 v[6:7], v[6:7], v[220:221]
	v_pk_mul_f32 v[8:9], v[108:109], v[30:31] op_sel_hi:[1,0]
	v_pk_mul_f32 v[6:7], v[6:7], v[16:17]
	v_pk_mul_f32 v[8:9], v[8:9], v[222:223]
	v_cvt_pk_bf16_f32 v6, v6, v7
	v_pk_mul_f32 v[8:9], v[8:9], v[24:25]
	s_waitcnt vmcnt(8)
	v_lshlrev_b32_e32 v16, 16, v224
	v_cvt_pk_bf16_f32 v7, v8, v9
	global_store_dwordx4 v[20:21], v[4:7], off offset:80
	s_nop 0
	v_and_b32_e32 v17, 0xffff0000, v224
	v_mul_f32_e32 v12, 0xbfb8aa3b, v16
	v_exp_f32_e32 v12, v12
	v_mul_f32_e32 v18, 0xbfb8aa3b, v17
	v_exp_f32_e32 v19, v18
	v_add_f32_e32 v12, 1.0, v12
	v_rcp_f32_e32 v18, v12
	v_add_f32_e32 v12, 1.0, v19
	v_rcp_f32_e32 v19, v12
	v_lshlrev_b32_e32 v12, 16, v225
	v_and_b32_e32 v13, 0xffff0000, v225
	v_pk_mul_f32 v[16:17], v[18:19], v[16:17]
	v_mul_f32_e32 v18, 0xbfb8aa3b, v12
	v_mul_f32_e32 v19, 0xbfb8aa3b, v13
	v_exp_f32_e32 v18, v18
	v_exp_f32_e32 v19, v19
	s_waitcnt vmcnt(8)
	v_pk_mul_f32 v[4:5], v[22:23], v[232:233]
	s_nop 0
	v_pk_mul_f32 v[4:5], v[4:5], v[16:17]
	v_add_f32_e32 v16, 1.0, v18
	v_add_f32_e32 v17, 1.0, v19
	v_rcp_f32_e32 v16, v16
	v_rcp_f32_e32 v17, v17
	v_cvt_pk_bf16_f32 v4, v4, v5
	v_pk_mul_f32 v[18:19], v[50:51], v[30:31] op_sel_hi:[1,0]
	v_pk_mul_f32 v[12:13], v[16:17], v[12:13]
	v_lshlrev_b32_e32 v16, 16, v226
	v_and_b32_e32 v17, 0xffff0000, v226
	v_mul_f32_e32 v5, 0xbfb8aa3b, v16
	v_exp_f32_e32 v5, v5
	v_mul_f32_e32 v14, 0xbfb8aa3b, v17
	v_exp_f32_e32 v14, v14
	v_pk_mul_f32 v[6:7], v[18:19], v[234:235]
	v_add_f32_e32 v5, 1.0, v5
	v_pk_mul_f32 v[6:7], v[6:7], v[12:13]
	v_rcp_f32_e32 v12, v5
	v_add_f32_e32 v5, 1.0, v14
	v_rcp_f32_e32 v13, v5
	v_cvt_pk_bf16_f32 v5, v6, v7
	v_pk_mul_f32 v[6:7], v[60:61], v[30:31] op_sel_hi:[1,0]
	s_waitcnt vmcnt(7)
	v_pk_mul_f32 v[6:7], v[6:7], v[236:237]
	v_pk_mul_f32 v[8:9], v[12:13], v[16:17]
	v_lshlrev_b32_e32 v12, 16, v227
	v_and_b32_e32 v13, 0xffff0000, v227
	v_mul_f32_e32 v14, 0xbfb8aa3b, v12
	v_mul_f32_e32 v15, 0xbfb8aa3b, v13
	v_exp_f32_e32 v14, v14
	v_exp_f32_e32 v15, v15
	v_pk_mul_f32 v[6:7], v[6:7], v[8:9]
	v_pk_mul_f32 v[16:17], v[36:37], v[30:31] op_sel_hi:[1,0]
	v_add_f32_e32 v8, 1.0, v14
	v_add_f32_e32 v9, 1.0, v15
	v_rcp_f32_e32 v8, v8
	v_rcp_f32_e32 v9, v9
	v_pk_mul_f32 v[14:15], v[68:69], v[30:31] op_sel_hi:[1,0]
	v_cvt_pk_bf16_f32 v6, v6, v7
	v_pk_mul_f32 v[10:11], v[14:15], v[238:239]
	v_pk_mul_f32 v[8:9], v[8:9], v[12:13]
	s_waitcnt vmcnt(5)
	v_lshlrev_b32_e32 v12, 16, v228
	v_pk_mul_f32 v[8:9], v[10:11], v[8:9]
	v_and_b32_e32 v13, 0xffff0000, v228
	v_cvt_pk_bf16_f32 v7, v8, v9
	global_store_dwordx4 v[20:21], v[4:7], off offset:96
	s_nop 0
	v_mul_f32_e32 v0, 0xbfb8aa3b, v12
	v_exp_f32_e32 v0, v0
	v_mul_f32_e32 v14, 0xbfb8aa3b, v13
	v_exp_f32_e32 v15, v14
	v_add_f32_e32 v0, 1.0, v0
	v_rcp_f32_e32 v14, v0
	v_add_f32_e32 v0, 1.0, v15
	v_rcp_f32_e32 v15, v0
	s_waitcnt vmcnt(5)
	v_pk_mul_f32 v[4:5], v[16:17], v[244:245]
	v_pk_mul_f32 v[12:13], v[14:15], v[12:13]
	v_lshlrev_b32_e32 v14, 16, v229
	v_and_b32_e32 v15, 0xffff0000, v229
	v_mul_f32_e32 v0, 0xbfb8aa3b, v14
	v_exp_f32_e32 v16, v0
	v_mul_f32_e32 v0, 0xbfb8aa3b, v15
	v_exp_f32_e32 v17, v0
	v_pk_mul_f32 v[0:1], v[4:5], v[12:13]
	v_pk_mul_f32 v[12:13], v[32:33], v[30:31] op_sel_hi:[1,0]
	v_add_f32_e32 v4, 1.0, v16
	v_pk_mul_f32 v[6:7], v[12:13], v[246:247]
	v_lshlrev_b32_e32 v12, 16, v230
	v_add_f32_e32 v5, 1.0, v17
	v_cvt_pk_bf16_f32 v0, v0, v1
	v_and_b32_e32 v13, 0xffff0000, v230
	v_mul_f32_e32 v1, 0xbfb8aa3b, v12
	v_rcp_f32_e32 v4, v4
	v_rcp_f32_e32 v5, v5
	v_exp_f32_e32 v1, v1
	v_mul_f32_e32 v2, 0xbfb8aa3b, v13
	v_exp_f32_e32 v2, v2
	v_pk_mul_f32 v[4:5], v[4:5], v[14:15]
	v_add_f32_e32 v1, 1.0, v1
	v_pk_mul_f32 v[4:5], v[6:7], v[4:5]
	v_rcp_f32_e32 v6, v1
	v_add_f32_e32 v1, 1.0, v2
	v_rcp_f32_e32 v7, v1
	v_cvt_pk_bf16_f32 v1, v4, v5
	v_pk_mul_f32 v[4:5], v[34:35], v[30:31] op_sel_hi:[1,0]
	v_pk_mul_f32 v[6:7], v[6:7], v[12:13]
	s_waitcnt vmcnt(4)
	v_pk_mul_f32 v[4:5], v[4:5], v[248:249]
	v_lshlrev_b32_e32 v8, 16, v231
	v_and_b32_e32 v9, 0xffff0000, v231
	v_mul_f32_e32 v2, 0xbfb8aa3b, v8
	v_exp_f32_e32 v12, v2
	v_mul_f32_e32 v2, 0xbfb8aa3b, v9
	v_exp_f32_e32 v13, v2
	v_pk_mul_f32 v[2:3], v[4:5], v[6:7]
	v_add_f32_e32 v4, 1.0, v12
	v_rcp_f32_e32 v4, v4
	v_add_f32_e32 v5, 1.0, v13
	v_rcp_f32_e32 v5, v5
	v_pk_mul_f32 v[6:7], v[38:39], v[30:31] op_sel_hi:[1,0]
	v_cvt_pk_bf16_f32 v2, v2, v3
	v_pk_mul_f32 v[6:7], v[6:7], v[250:251]
	v_pk_mul_f32 v[4:5], v[4:5], v[8:9]
	s_nop 0
	v_pk_mul_f32 v[4:5], v[6:7], v[4:5]
	s_nop 0
	v_cvt_pk_bf16_f32 v3, v4, v5
	global_store_dwordx4 v[20:21], v[0:3], off offset:112
	s_barrier
	s_load_dword s2, s[38:39], 0x0
	s_waitcnt lgkmcnt(0)
	s_add_i32 s89, s2, s89
	s_cmpk_gt_i32 s89, 0xff
	s_cbranch_scc1 .LBB0_202
